# code placement variant: GEMM loop heads at hipcc phase, attention loop head at phase 0
# speedup vs baseline: 1.0089x; 1.0017x over previous
.LBB0_596:
	s_and_b32 s54, s2, 7
	s_add_i32 s2, s3, s37
	s_ashr_i32 s3, s2, 31
	s_mul_i32 s42, s2, 0xc00
	s_mul_hi_i32 s19, s2, 0xc00
	s_add_u32 s42, s22, s42
	s_addc_u32 s19, s23, s19
	s_mul_i32 s44, s54, 0x180
	s_add_u32 s44, s42, s44
	s_addc_u32 s45, s19, 0
	s_ashr_i32 s19, s18, 31
	v_lshl_add_u64 v[2:3], s[44:45], 0, v[170:171]
	s_lshl_b64 s[44:45], s[18:19], 11
	s_add_u32 s46, s25, s44
	s_addc_u32 s47, s26, s45
	s_lshl_b32 s42, s54, 7
	s_lshl_b32 s56, s54, 8
	s_add_u32 s46, s46, s56
	s_addc_u32 s47, s47, 0
	s_lshl_b64 s[48:49], s[18:19], 7
	s_add_u32 s50, s17, s48
	s_addc_u32 s51, s21, s49
	s_mul_i32 s57, s54, 0x580000
	s_add_u32 s60, s27, s57
	s_addc_u32 s61, s30, 0
	s_lshl_b64 s[54:55], s[18:19], 1
	s_add_u32 s18, s60, s54
	s_addc_u32 s19, s61, s55
	s_add_i32 s60, s39, 0
	global_load_dwordx4 v[156:159], v[2:3], off
	global_load_dwordx4 v[152:155], v[2:3], off offset:32
	global_load_dwordx4 v[148:151], v[2:3], off offset:64
	global_load_dwordx4 v[144:147], v[2:3], off offset:96
	global_load_dwordx4 v[140:143], v[2:3], off offset:128
	global_load_dwordx4 v[136:139], v[2:3], off offset:160
	global_load_dwordx4 v[132:135], v[2:3], off offset:192
	global_load_dwordx4 v[128:131], v[2:3], off offset:224
	global_load_dwordx4 v[124:127], v[2:3], off offset:256
	global_load_dwordx4 v[120:123], v[2:3], off offset:288
	global_load_dwordx4 v[116:119], v[2:3], off offset:320
	global_load_dwordx4 v[112:115], v[2:3], off offset:352
	s_waitcnt lgkmcnt(0)
	s_barrier
	v_lshl_add_u64 v[2:3], s[46:47], 0, v[166:167]
	s_mov_b32 m0, s60
	v_lshl_add_u64 v[4:5], s[18:19], 0, v[160:161]
	global_load_lds_dwordx4 v[2:3], off
	v_lshl_add_u64 v[2:3], s[46:47], 0, v[168:169]
	s_add_i32 m0, s60, 0x400
	v_lshl_add_u64 v[6:7], s[18:19], 0, v[162:163]
	global_load_lds_dwordx4 v[2:3], off
	v_lshl_add_u64 v[2:3], s[50:51], 0, v[164:165]
	s_add_i32 s50, s41, 0
	s_add_i32 m0, s50, 0x4000
	v_mov_b32_e32 v14, v1
	global_load_lds_dwordx4 v[2:3], off
	s_add_i32 m0, s60, 0x6000
	v_lshl_add_u64 v[2:3], v[2:3], 0, s[28:29]
	global_load_lds_dwordx4 v[4:5], off
	s_add_i32 m0, s60, 0x6400
	s_add_u32 s18, s46, 0x20000
	s_addc_u32 s19, s47, 0
	global_load_lds_dwordx4 v[6:7], off
	v_lshl_add_u64 v[8:9], s[18:19], 0, v[166:167]
	s_add_i32 m0, s60, 0xa000
	v_mov_b32_e32 v15, v1
	global_load_lds_dwordx4 v[8:9], off
	v_lshl_add_u64 v[8:9], s[18:19], 0, v[168:169]
	s_add_i32 m0, s60, 0xa400
	s_add_i32 s18, 0, 0x10000
	global_load_lds_dwordx4 v[8:9], off
	s_add_i32 m0, s50, 0xe000
	v_mov_b32_e32 v0, v1
	global_load_lds_dwordx4 v[2:3], off
	v_lshl_add_u64 v[2:3], v[4:5], 0, s[76:77]
	s_add_i32 m0, s18, s39
	v_mov_b32_e32 v4, v1
	global_load_lds_dwordx4 v[2:3], off
	v_lshl_add_u64 v[2:3], v[6:7], 0, s[76:77]
	s_add_i32 m0, s18, s40
	s_add_u32 s46, s54, s57
	global_load_lds_dwordx4 v[2:3], off
	s_addc_u32 s47, s55, 0
	s_or_b32 s44, s44, s56
	v_mov_b32_e32 v2, v1
	v_mov_b32_e32 v3, v1
	v_mov_b32_e32 v5, v1
	v_mov_b32_e32 v6, v1
	v_mov_b32_e32 v7, v1
	v_mov_b32_e32 v8, v1
	v_mov_b32_e32 v9, v1
	v_mov_b32_e32 v10, v1
	v_mov_b32_e32 v11, v1
	v_mov_b32_e32 v12, v1
	v_mov_b32_e32 v13, v1
	v_mov_b64_e32 v[30:31], v[14:15]
	v_mov_b64_e32 v[46:47], v[14:15]
	v_mov_b64_e32 v[62:63], v[14:15]
	v_mov_b64_e32 v[78:79], v[14:15]
	v_readlane_b32 s54, v255, 36
	s_mov_b32 s19, 1
	v_lshl_add_u64 v[204:205], s[46:47], 0, v[194:195]
	v_lshl_add_u64 v[206:207], s[46:47], 0, v[196:197]
	v_lshl_add_u64 v[208:209], v[198:199], 0, s[48:49]
	v_lshl_add_u64 v[210:211], s[44:45], 0, v[200:201]
	v_lshl_add_u64 v[212:213], s[44:45], 0, v[202:203]
	s_mov_b32 s18, 0
	v_mov_b32_e32 v220, 0
	v_mov_b32_e32 v221, 0xf149f2ca
	v_mov_b64_e32 v[28:29], v[12:13]
	v_mov_b64_e32 v[26:27], v[10:11]
	v_mov_b64_e32 v[24:25], v[8:9]
	v_mov_b64_e32 v[22:23], v[6:7]
	v_mov_b64_e32 v[20:21], v[4:5]
	v_mov_b64_e32 v[18:19], v[2:3]
	v_mov_b64_e32 v[16:17], v[0:1]
	v_mov_b64_e32 v[44:45], v[12:13]
	v_mov_b64_e32 v[42:43], v[10:11]
	v_mov_b64_e32 v[40:41], v[8:9]
	v_mov_b64_e32 v[38:39], v[6:7]
	v_mov_b64_e32 v[36:37], v[4:5]
	v_mov_b64_e32 v[34:35], v[2:3]
	v_mov_b64_e32 v[32:33], v[0:1]
	v_mov_b64_e32 v[60:61], v[12:13]
	v_mov_b64_e32 v[58:59], v[10:11]
	v_mov_b64_e32 v[56:57], v[8:9]
	v_mov_b64_e32 v[54:55], v[6:7]
	v_mov_b64_e32 v[52:53], v[4:5]
	v_mov_b64_e32 v[50:51], v[2:3]
	v_mov_b64_e32 v[48:49], v[0:1]
	v_mov_b64_e32 v[76:77], v[12:13]
	v_mov_b64_e32 v[74:75], v[10:11]
	v_mov_b64_e32 v[72:73], v[8:9]
	v_mov_b64_e32 v[70:71], v[6:7]
	v_mov_b64_e32 v[68:69], v[4:5]
	v_mov_b64_e32 v[66:67], v[2:3]
	v_mov_b64_e32 v[64:65], v[0:1]
	v_readlane_b32 s55, v255, 37
	v_readlane_b32 s56, v254, 6
	s_mov_b32 s60, 0x1c000
	v_readlane_b32 s57, v254, 7
	s_waitcnt vmcnt(5)
	s_nop 0

.Lh13_b:
	s_ashr_i32 s37, s36, 31
	s_lshl_b64 s[18:19], s[36:37], 19
	s_add_u32 s62, s22, s18
	v_mov_b32_e32 v141, 0
	s_addc_u32 s63, s23, s19
	s_andn2_b64 vcc, exec, s[46:47]
	s_waitcnt lgkmcnt(0)
	s_cbranch_vccnz .LBB0_693
	s_and_b64 s[18:19], s[42:43], exec
	s_cselect_b32 s1, s61, s27
	s_cselect_b32 s37, s60, s26
	s_cselect_b32 s57, s63, s3
	s_cselect_b32 s89, s62, s2
	s_add_u32 vcc_lo, s26, 0x100
	s_addc_u32 vcc_hi, s27, 0
	s_add_u32 s90, s2, 0x100
	s_addc_u32 s91, s3, 0
	s_add_u32 s2, s26, 0x40080
	v_mov_b32_e32 v2, 0
	s_addc_u32 s3, s27, 0
	s_mov_b32 s18, 0
	v_mov_b32_e32 v3, v2
	v_mov_b32_e32 v4, v2
	v_mov_b32_e32 v5, v2
	v_mov_b32_e32 v6, v2
	v_mov_b32_e32 v7, v2
	v_mov_b32_e32 v8, v2
	v_mov_b32_e32 v9, v2
	v_mov_b32_e32 v18, v2
	v_mov_b32_e32 v19, v2
	v_mov_b32_e32 v20, v2
	v_mov_b32_e32 v21, v2
	v_mov_b32_e32 v22, v2
	v_mov_b32_e32 v23, v2
	v_mov_b32_e32 v24, v2
	v_mov_b32_e32 v25, v2
	v_mov_b32_e32 v34, v2
	v_mov_b32_e32 v35, v2
	v_mov_b32_e32 v36, v2
	v_mov_b32_e32 v37, v2
	v_mov_b32_e32 v38, v2
	v_mov_b32_e32 v39, v2
	v_mov_b32_e32 v40, v2
	v_mov_b32_e32 v41, v2
	v_mov_b32_e32 v50, v2
	v_mov_b32_e32 v51, v2
	v_mov_b32_e32 v52, v2
	v_mov_b32_e32 v53, v2
	v_mov_b32_e32 v54, v2
	v_mov_b32_e32 v55, v2
	v_mov_b32_e32 v56, v2
	v_mov_b32_e32 v57, v2
	v_mov_b32_e32 v10, v2
	v_mov_b32_e32 v11, v2
	v_mov_b32_e32 v12, v2
	v_mov_b32_e32 v13, v2
	v_mov_b32_e32 v14, v2
	v_mov_b32_e32 v15, v2
	v_mov_b32_e32 v16, v2
	v_mov_b32_e32 v17, v2
	v_mov_b32_e32 v26, v2
	v_mov_b32_e32 v27, v2
	v_mov_b32_e32 v28, v2
	v_mov_b32_e32 v29, v2
	v_mov_b32_e32 v30, v2
	v_mov_b32_e32 v31, v2
	v_mov_b32_e32 v32, v2
	v_mov_b32_e32 v33, v2
	v_mov_b32_e32 v42, v2
	v_mov_b32_e32 v43, v2
	v_mov_b32_e32 v44, v2
	v_mov_b32_e32 v45, v2
	v_mov_b32_e32 v46, v2
	v_mov_b32_e32 v47, v2
	v_mov_b32_e32 v48, v2
	v_mov_b32_e32 v49, v2
	v_mov_b32_e32 v58, v2
	v_mov_b32_e32 v59, v2
	v_mov_b32_e32 v60, v2
	v_mov_b32_e32 v61, v2
	v_mov_b32_e32 v62, v2
	v_mov_b32_e32 v63, v2
	v_mov_b32_e32 v64, v2
	v_mov_b32_e32 v65, v2
	v_mov_b32_e32 v82, v2
	v_mov_b32_e32 v83, v2
	v_mov_b32_e32 v84, v2
	v_mov_b32_e32 v85, v2
	v_mov_b32_e32 v86, v2
	v_mov_b32_e32 v87, v2
	v_mov_b32_e32 v88, v2
	v_mov_b32_e32 v89, v2
	v_mov_b32_e32 v98, v2
	v_mov_b32_e32 v99, v2
	v_mov_b32_e32 v100, v2
	v_mov_b32_e32 v101, v2
	v_mov_b32_e32 v102, v2
	v_mov_b32_e32 v103, v2
	v_mov_b32_e32 v104, v2
	v_mov_b32_e32 v105, v2
	v_mov_b32_e32 v114, v2
	v_mov_b32_e32 v115, v2
	v_mov_b32_e32 v116, v2
	v_mov_b32_e32 v117, v2
	v_mov_b32_e32 v118, v2
	v_mov_b32_e32 v119, v2
	v_mov_b32_e32 v120, v2
	v_mov_b32_e32 v121, v2
	v_mov_b32_e32 v130, v2
	v_mov_b32_e32 v131, v2
	v_mov_b32_e32 v132, v2
	v_mov_b32_e32 v133, v2
	v_mov_b32_e32 v134, v2
	v_mov_b32_e32 v135, v2
	v_mov_b32_e32 v136, v2
	v_mov_b32_e32 v137, v2
	v_mov_b32_e32 v90, v2
	v_mov_b32_e32 v91, v2
	v_mov_b32_e32 v92, v2
	v_mov_b32_e32 v93, v2
	v_mov_b32_e32 v94, v2
	v_mov_b32_e32 v95, v2
	v_mov_b32_e32 v96, v2
	v_mov_b32_e32 v97, v2
	v_mov_b32_e32 v106, v2
	v_mov_b32_e32 v107, v2
	v_mov_b32_e32 v108, v2
	v_mov_b32_e32 v109, v2
	v_mov_b32_e32 v110, v2
	v_mov_b32_e32 v111, v2
	v_mov_b32_e32 v112, v2
	v_mov_b32_e32 v113, v2
	v_mov_b32_e32 v122, v2
	v_mov_b32_e32 v123, v2
	v_mov_b32_e32 v124, v2
	v_mov_b32_e32 v125, v2
	v_mov_b32_e32 v126, v2
	v_mov_b32_e32 v127, v2
	v_mov_b32_e32 v128, v2
	v_mov_b32_e32 v129, v2
	v_mov_b32_e32 v142, v2
	v_mov_b32_e32 v143, v2
	v_mov_b32_e32 v144, v2
	v_mov_b32_e32 v145, v2
	v_mov_b32_e32 v138, v2
	v_mov_b32_e32 v139, v2
	v_mov_b32_e32 v140, v2
	v_mov_b32_e32 v141, v2
	s_nop 0
